# E25: E23 + P0 adaLN batch loop keeps two batches of 16 weight loads in flight (double-buffered regs, unrolled by two, counted vmcnt)
# speedup vs baseline: 1.0047x; 1.0047x over previous
; __global__ void __launch_bounds__(NWAVES * 64, 2) mk_fwd(Args args) {
;     ...
;             for (int it = vcu; it < DEPTH * 192; it += G) { const int l = it / 192, c0 = (it % 192) * 32;
;                 const float* wp = w_ada + (size_t)l * DMODEL * 6144 + c0 + (lane & 31); const int kofs = 2 * wave + (lane >> 5);
;                 float a0 = 0.f, a1 = 0.f, a2 = 0.f, a3 = 0.f;
; #pragma unroll 1
;                 for (int j = 0; j < 128; j += 16) {
;                     float wv[16];
; #pragma unroll
;                     for (int q = 0; q < 16; ++q) wv[q] = __builtin_nontemporal_load(wp + (size_t)(16 * (j + q) + kofs) * 6144);
; #pragma unroll
;                     for (int q = 0; q < 16; q += 4) { a0 += cond[16 * (j + q) + kofs] * wv[q]; a1 += cond[16 * (j + q + 1) + kofs] * wv[q + 1];
;                         a2 += cond[16 * (j + q + 2) + kofs] * wv[q + 2]; a3 += cond[16 * (j + q + 3) + kofs] * wv[q + 3]; }
;                 }
.LBB0_19:
	s_mul_hi_i32 s2, s1, 0x2aaaaaab
	s_lshr_b32 s18, s2, 31
	s_ashr_i32 s2, s2, 5
	s_add_i32 s2, s2, s18
	s_mul_i32 s18, s2, 0xc0
	s_sub_i32 s18, s1, s18
	s_lshl_b32 s18, s18, 5
	s_ashr_i32 s19, s18, 31
	s_mul_i32 s23, s2, 0x3000000
	s_lshl_b64 s[20:21], s[18:19], 2
	s_mul_hi_i32 s22, s2, 0x3000000
	s_add_u32 s20, s23, s20
	s_addc_u32 s21, s22, s21
	v_lshl_add_u64 v[38:39], v[6:7], 0, s[20:21]
	v_lshl_add_u64 v[40:41], v[8:9], 0, s[20:21]
	v_lshl_add_u64 v[42:43], v[10:11], 0, s[20:21]
	v_lshl_add_u64 v[44:45], v[12:13], 0, s[20:21]
	v_lshl_add_u64 v[46:47], v[14:15], 0, s[20:21]
	v_lshl_add_u64 v[48:49], v[16:17], 0, s[20:21]
	v_lshl_add_u64 v[50:51], v[18:19], 0, s[20:21]
	v_lshl_add_u64 v[52:53], v[20:21], 0, s[20:21]
	v_lshl_add_u64 v[54:55], v[22:23], 0, s[20:21]
	v_lshl_add_u64 v[56:57], v[24:25], 0, s[20:21]
	v_lshl_add_u64 v[58:59], v[26:27], 0, s[20:21]
	v_lshl_add_u64 v[60:61], v[28:29], 0, s[20:21]
	v_lshl_add_u64 v[62:63], v[30:31], 0, s[20:21]
	v_lshl_add_u64 v[64:65], v[32:33], 0, s[20:21]
	v_lshl_add_u64 v[66:67], v[34:35], 0, s[20:21]
	v_lshl_add_u64 v[68:69], v[36:37], 0, s[20:21]
	s_mov_b32 s19, -16
	v_mov_b32_e32 v77, v76
	v_mov_b32_e32 v70, 0
	v_mov_b32_e32 v71, v5
	v_mov_b32_e32 v72, 0
	v_mov_b32_e32 v73, v5
	v_lshl_add_u64 v[78:79], v[68:69], 0, v[4:5]
	v_lshl_add_u64 v[80:81], v[66:67], 0, v[4:5]
	v_lshl_add_u64 v[82:83], v[64:65], 0, v[4:5]
	v_lshl_add_u64 v[84:85], v[62:63], 0, v[4:5]
	v_lshl_add_u64 v[86:87], v[42:43], 0, v[4:5]
	v_lshl_add_u64 v[88:89], v[60:61], 0, v[4:5]
	v_lshl_add_u64 v[90:91], v[58:59], 0, v[4:5]
	v_lshl_add_u64 v[92:93], v[56:57], 0, v[4:5]
	v_lshl_add_u64 v[94:95], v[40:41], 0, v[4:5]
	v_lshl_add_u64 v[96:97], v[54:55], 0, v[4:5]
	v_lshl_add_u64 v[98:99], v[52:53], 0, v[4:5]
	v_lshl_add_u64 v[100:101], v[50:51], 0, v[4:5]
	v_lshl_add_u64 v[102:103], v[38:39], 0, v[4:5]
	v_lshl_add_u64 v[104:105], v[48:49], 0, v[4:5]
	v_lshl_add_u64 v[106:107], v[46:47], 0, v[4:5]
	v_lshl_add_u64 v[108:109], v[44:45], 0, v[4:5]
	global_load_dword v111, v[78:79], off nt
	global_load_dword v113, v[80:81], off nt
	global_load_dword v110, v[82:83], off nt
	global_load_dword v112, v[84:85], off nt
	global_load_dword v115, v[86:87], off nt
	global_load_dword v117, v[88:89], off nt
	global_load_dword v114, v[90:91], off nt
	global_load_dword v116, v[92:93], off nt
	global_load_dword v119, v[94:95], off nt
	global_load_dword v121, v[96:97], off nt
	global_load_dword v118, v[98:99], off nt
	global_load_dword v120, v[100:101], off nt
	global_load_dword v123, v[102:103], off nt
	global_load_dword v125, v[104:105], off nt
	global_load_dword v122, v[106:107], off nt
	global_load_dword v124, v[108:109], off nt
	v_lshl_add_u64 v[38:39], v[38:39], 0, s[6:7]
	v_lshl_add_u64 v[40:41], v[40:41], 0, s[6:7]
	v_lshl_add_u64 v[42:43], v[42:43], 0, s[6:7]
	v_lshl_add_u64 v[44:45], v[44:45], 0, s[6:7]
	v_lshl_add_u64 v[46:47], v[46:47], 0, s[6:7]
	v_lshl_add_u64 v[48:49], v[48:49], 0, s[6:7]
	v_lshl_add_u64 v[50:51], v[50:51], 0, s[6:7]
	v_lshl_add_u64 v[52:53], v[52:53], 0, s[6:7]
	v_lshl_add_u64 v[54:55], v[54:55], 0, s[6:7]
	v_lshl_add_u64 v[56:57], v[56:57], 0, s[6:7]
	v_lshl_add_u64 v[58:59], v[58:59], 0, s[6:7]
	v_lshl_add_u64 v[60:61], v[60:61], 0, s[6:7]
	v_lshl_add_u64 v[62:63], v[62:63], 0, s[6:7]
	v_lshl_add_u64 v[64:65], v[64:65], 0, s[6:7]
	v_lshl_add_u64 v[66:67], v[66:67], 0, s[6:7]
	v_lshl_add_u64 v[68:69], v[68:69], 0, s[6:7]
.LBB0_20:
	v_lshl_add_u64 v[78:79], v[68:69], 0, v[4:5]
	v_lshl_add_u64 v[80:81], v[66:67], 0, v[4:5]
	v_lshl_add_u64 v[82:83], v[64:65], 0, v[4:5]
	v_lshl_add_u64 v[84:85], v[62:63], 0, v[4:5]
	v_lshl_add_u64 v[86:87], v[42:43], 0, v[4:5]
	v_lshl_add_u64 v[88:89], v[60:61], 0, v[4:5]
	v_lshl_add_u64 v[90:91], v[58:59], 0, v[4:5]
	v_lshl_add_u64 v[92:93], v[56:57], 0, v[4:5]
	v_lshl_add_u64 v[94:95], v[40:41], 0, v[4:5]
	v_lshl_add_u64 v[96:97], v[54:55], 0, v[4:5]
	v_lshl_add_u64 v[98:99], v[52:53], 0, v[4:5]
	v_lshl_add_u64 v[100:101], v[50:51], 0, v[4:5]
	v_lshl_add_u64 v[102:103], v[38:39], 0, v[4:5]
	v_lshl_add_u64 v[104:105], v[48:49], 0, v[4:5]
	v_lshl_add_u64 v[106:107], v[46:47], 0, v[4:5]
	v_lshl_add_u64 v[108:109], v[44:45], 0, v[4:5]
	global_load_dword v127, v[78:79], off nt
	global_load_dword v129, v[80:81], off nt
	global_load_dword v126, v[82:83], off nt
	global_load_dword v128, v[84:85], off nt
	global_load_dword v131, v[86:87], off nt
	global_load_dword v133, v[88:89], off nt
	global_load_dword v130, v[90:91], off nt
	global_load_dword v132, v[92:93], off nt
	global_load_dword v135, v[94:95], off nt
	global_load_dword v137, v[96:97], off nt
	global_load_dword v134, v[98:99], off nt
	global_load_dword v136, v[100:101], off nt
	global_load_dword v139, v[102:103], off nt
	global_load_dword v141, v[104:105], off nt
	global_load_dword v138, v[106:107], off nt
	global_load_dword v140, v[108:109], off nt
	v_lshl_add_u64 v[38:39], v[38:39], 0, s[6:7]
	v_lshl_add_u64 v[40:41], v[40:41], 0, s[6:7]
	v_lshl_add_u64 v[42:43], v[42:43], 0, s[6:7]
	v_lshl_add_u64 v[44:45], v[44:45], 0, s[6:7]
	v_lshl_add_u64 v[46:47], v[46:47], 0, s[6:7]
	v_lshl_add_u64 v[48:49], v[48:49], 0, s[6:7]
	v_lshl_add_u64 v[50:51], v[50:51], 0, s[6:7]
	v_lshl_add_u64 v[52:53], v[52:53], 0, s[6:7]
	v_lshl_add_u64 v[54:55], v[54:55], 0, s[6:7]
	v_lshl_add_u64 v[56:57], v[56:57], 0, s[6:7]
	v_lshl_add_u64 v[58:59], v[58:59], 0, s[6:7]
	v_lshl_add_u64 v[60:61], v[60:61], 0, s[6:7]
	v_lshl_add_u64 v[62:63], v[62:63], 0, s[6:7]
	v_lshl_add_u64 v[64:65], v[64:65], 0, s[6:7]
	v_lshl_add_u64 v[66:67], v[66:67], 0, s[6:7]
	v_lshl_add_u64 v[68:69], v[68:69], 0, s[6:7]
	ds_read2_b32 v[78:79], v77 offset1:16
	ds_read2_b32 v[80:81], v77 offset0:32 offset1:48
	ds_read2_b32 v[82:83], v77 offset0:64 offset1:80
	ds_read2_b32 v[84:85], v77 offset0:96 offset1:112
	ds_read2_b32 v[86:87], v77 offset0:128 offset1:144
	ds_read2_b32 v[88:89], v77 offset0:160 offset1:176
	ds_read2_b32 v[90:91], v77 offset0:192 offset1:208
	ds_read2_b32 v[92:93], v77 offset0:224 offset1:240
	s_waitcnt lgkmcnt(6)
; __global__ void __launch_bounds__(NWAVES * 64, 2) mk_fwd(Args args) {
;     ...
;                 for (int j = 0; j < 128; j += 16) {
;                     float wv[16];
; #pragma unroll
;                     for (int q = 0; q < 16; ++q) wv[q] = __builtin_nontemporal_load(wp + (size_t)(16 * (j + q) + kofs) * 6144);
; #pragma unroll
;                     for (int q = 0; q < 16; q += 4) { a0 += cond[16 * (j + q) + kofs] * wv[q]; a1 += cond[16 * (j + q + 1) + kofs] * wv[q + 1];
;                         a2 += cond[16 * (j + q + 2) + kofs] * wv[q + 2]; a3 += cond[16 * (j + q + 3) + kofs] * wv[q + 3]; }
;                 }
	v_mov_b32_e32 v94, v80
	v_mov_b32_e32 v95, v78
	v_mov_b32_e32 v78, v81
	s_waitcnt lgkmcnt(4)
	v_mov_b32_e32 v80, v84
	v_mov_b32_e32 v81, v82
	v_mov_b32_e32 v82, v85
	s_waitcnt lgkmcnt(2)
	v_mov_b32_e32 v84, v88
	v_mov_b32_e32 v85, v86
	v_mov_b32_e32 v86, v89
	s_add_i32 s19, s19, 16
	s_waitcnt lgkmcnt(0)
	v_mov_b32_e32 v88, v92
	v_mov_b32_e32 v89, v90
	v_mov_b32_e32 v90, v93
	v_add_u32_e32 v77, 0x400, v77
	s_waitcnt vmcnt(29)
	v_pk_fma_f32 v[72:73], v[94:95], v[110:111], v[72:73]
	s_waitcnt vmcnt(28)
	v_pk_fma_f32 v[70:71], v[78:79], v[112:113], v[70:71]
	s_waitcnt vmcnt(25)
	v_pk_fma_f32 v[72:73], v[80:81], v[114:115], v[72:73]
	s_waitcnt vmcnt(24)
	v_pk_fma_f32 v[70:71], v[82:83], v[116:117], v[70:71]
	s_waitcnt vmcnt(21)
	v_pk_fma_f32 v[72:73], v[84:85], v[118:119], v[72:73]
	s_waitcnt vmcnt(20)
	v_pk_fma_f32 v[70:71], v[86:87], v[120:121], v[70:71]
	s_waitcnt vmcnt(17)
	v_pk_fma_f32 v[72:73], v[88:89], v[122:123], v[72:73]
	s_waitcnt vmcnt(16)
	v_pk_fma_f32 v[70:71], v[90:91], v[124:125], v[70:71]
	s_cmpk_gt_u32 s19, 0x5f
	s_cbranch_scc1 .Lada_last
	v_lshl_add_u64 v[78:79], v[68:69], 0, v[4:5]
	v_lshl_add_u64 v[80:81], v[66:67], 0, v[4:5]
	v_lshl_add_u64 v[82:83], v[64:65], 0, v[4:5]
	v_lshl_add_u64 v[84:85], v[62:63], 0, v[4:5]
	v_lshl_add_u64 v[86:87], v[42:43], 0, v[4:5]
	v_lshl_add_u64 v[88:89], v[60:61], 0, v[4:5]
	v_lshl_add_u64 v[90:91], v[58:59], 0, v[4:5]
	v_lshl_add_u64 v[92:93], v[56:57], 0, v[4:5]
	v_lshl_add_u64 v[94:95], v[40:41], 0, v[4:5]
	v_lshl_add_u64 v[96:97], v[54:55], 0, v[4:5]
	v_lshl_add_u64 v[98:99], v[52:53], 0, v[4:5]
	v_lshl_add_u64 v[100:101], v[50:51], 0, v[4:5]
	v_lshl_add_u64 v[102:103], v[38:39], 0, v[4:5]
	v_lshl_add_u64 v[104:105], v[48:49], 0, v[4:5]
	v_lshl_add_u64 v[106:107], v[46:47], 0, v[4:5]
	v_lshl_add_u64 v[108:109], v[44:45], 0, v[4:5]
	global_load_dword v111, v[78:79], off nt
	global_load_dword v113, v[80:81], off nt
	global_load_dword v110, v[82:83], off nt
	global_load_dword v112, v[84:85], off nt
	global_load_dword v115, v[86:87], off nt
	global_load_dword v117, v[88:89], off nt
	global_load_dword v114, v[90:91], off nt
	global_load_dword v116, v[92:93], off nt
	global_load_dword v119, v[94:95], off nt
	global_load_dword v121, v[96:97], off nt
	global_load_dword v118, v[98:99], off nt
	global_load_dword v120, v[100:101], off nt
	global_load_dword v123, v[102:103], off nt
	global_load_dword v125, v[104:105], off nt
	global_load_dword v122, v[106:107], off nt
	global_load_dword v124, v[108:109], off nt
	v_lshl_add_u64 v[38:39], v[38:39], 0, s[6:7]
	v_lshl_add_u64 v[40:41], v[40:41], 0, s[6:7]
	v_lshl_add_u64 v[42:43], v[42:43], 0, s[6:7]
	v_lshl_add_u64 v[44:45], v[44:45], 0, s[6:7]
	v_lshl_add_u64 v[46:47], v[46:47], 0, s[6:7]
	v_lshl_add_u64 v[48:49], v[48:49], 0, s[6:7]
	v_lshl_add_u64 v[50:51], v[50:51], 0, s[6:7]
	v_lshl_add_u64 v[52:53], v[52:53], 0, s[6:7]
	v_lshl_add_u64 v[54:55], v[54:55], 0, s[6:7]
	v_lshl_add_u64 v[56:57], v[56:57], 0, s[6:7]
	v_lshl_add_u64 v[58:59], v[58:59], 0, s[6:7]
	v_lshl_add_u64 v[60:61], v[60:61], 0, s[6:7]
	v_lshl_add_u64 v[62:63], v[62:63], 0, s[6:7]
	v_lshl_add_u64 v[64:65], v[64:65], 0, s[6:7]
	v_lshl_add_u64 v[66:67], v[66:67], 0, s[6:7]
	v_lshl_add_u64 v[68:69], v[68:69], 0, s[6:7]
	ds_read2_b32 v[78:79], v77 offset1:16
	ds_read2_b32 v[80:81], v77 offset0:32 offset1:48
	ds_read2_b32 v[82:83], v77 offset0:64 offset1:80
	ds_read2_b32 v[84:85], v77 offset0:96 offset1:112
	ds_read2_b32 v[86:87], v77 offset0:128 offset1:144
	ds_read2_b32 v[88:89], v77 offset0:160 offset1:176
	ds_read2_b32 v[90:91], v77 offset0:192 offset1:208
	ds_read2_b32 v[92:93], v77 offset0:224 offset1:240
	s_waitcnt lgkmcnt(6)
	v_mov_b32_e32 v94, v80
	v_mov_b32_e32 v95, v78
	v_mov_b32_e32 v78, v81
	s_waitcnt lgkmcnt(4)
	v_mov_b32_e32 v80, v84
	v_mov_b32_e32 v81, v82
	v_mov_b32_e32 v82, v85
	s_waitcnt lgkmcnt(2)
	v_mov_b32_e32 v84, v88
	v_mov_b32_e32 v85, v86
	v_mov_b32_e32 v86, v89
	s_add_i32 s19, s19, 16
	s_waitcnt lgkmcnt(0)
	v_mov_b32_e32 v88, v92
	v_mov_b32_e32 v89, v90
	v_mov_b32_e32 v90, v93
	v_add_u32_e32 v77, 0x400, v77
	s_waitcnt vmcnt(29)
	v_pk_fma_f32 v[72:73], v[94:95], v[126:127], v[72:73]
	s_waitcnt vmcnt(28)
	v_pk_fma_f32 v[70:71], v[78:79], v[128:129], v[70:71]
	s_waitcnt vmcnt(25)
	v_pk_fma_f32 v[72:73], v[80:81], v[130:131], v[72:73]
	s_waitcnt vmcnt(24)
	v_pk_fma_f32 v[70:71], v[82:83], v[132:133], v[70:71]
	s_waitcnt vmcnt(21)
	v_pk_fma_f32 v[72:73], v[84:85], v[134:135], v[72:73]
	s_waitcnt vmcnt(20)
	v_pk_fma_f32 v[70:71], v[86:87], v[136:137], v[70:71]
	s_waitcnt vmcnt(17)
	v_pk_fma_f32 v[72:73], v[88:89], v[138:139], v[72:73]
	s_waitcnt vmcnt(16)
	v_pk_fma_f32 v[70:71], v[90:91], v[140:141], v[70:71]
	s_branch .LBB0_20
; __global__ void __launch_bounds__(NWAVES * 64, 2) mk_fwd(Args args) {
;     ...
;                 for (int j = 0; j < 128; j += 16) {
;                     float wv[16];
; #pragma unroll
;                     for (int q = 0; q < 16; ++q) wv[q] = __builtin_nontemporal_load(wp + (size_t)(16 * (j + q) + kofs) * 6144);
; #pragma unroll
;                     for (int q = 0; q < 16; q += 4) { a0 += cond[16 * (j + q) + kofs] * wv[q]; a1 += cond[16 * (j + q + 1) + kofs] * wv[q + 1];
;                         a2 += cond[16 * (j + q + 2) + kofs] * wv[q + 2]; a3 += cond[16 * (j + q + 3) + kofs] * wv[q + 3]; }
;                 }
;                 red[(2 * wave + (lane >> 5)) * 32 + (lane & 31)] = (a0 + a1) + (a2 + a3);
;                 __syncthreads();
;                 if (tid < 32) { float s = b_ada[l * 6144 + c0 + tid];
; #pragma unroll
;                     for (int p = 0; p < 16; ++p) s += red[p * 32 + tid];
;                     MODV[l * 6144 + c0 + tid] = s; }
;                 __syncthreads();
.Lada_last:
	ds_read2_b32 v[78:79], v77 offset1:16
	ds_read2_b32 v[80:81], v77 offset0:32 offset1:48
	ds_read2_b32 v[82:83], v77 offset0:64 offset1:80
	ds_read2_b32 v[84:85], v77 offset0:96 offset1:112
	ds_read2_b32 v[86:87], v77 offset0:128 offset1:144
	ds_read2_b32 v[88:89], v77 offset0:160 offset1:176
	ds_read2_b32 v[90:91], v77 offset0:192 offset1:208
	ds_read2_b32 v[92:93], v77 offset0:224 offset1:240
	s_waitcnt lgkmcnt(6)
	v_mov_b32_e32 v94, v80
	v_mov_b32_e32 v95, v78
	v_mov_b32_e32 v78, v81
	s_waitcnt lgkmcnt(4)
	v_mov_b32_e32 v80, v84
	v_mov_b32_e32 v81, v82
	v_mov_b32_e32 v82, v85
	s_waitcnt lgkmcnt(2)
	v_mov_b32_e32 v84, v88
	v_mov_b32_e32 v85, v86
	v_mov_b32_e32 v86, v89
	s_add_i32 s19, s19, 16
	s_waitcnt lgkmcnt(0)
	v_mov_b32_e32 v88, v92
	v_mov_b32_e32 v89, v90
	v_mov_b32_e32 v90, v93
	v_add_u32_e32 v77, 0x400, v77
	s_waitcnt vmcnt(13)
	v_pk_fma_f32 v[72:73], v[94:95], v[126:127], v[72:73]
	s_waitcnt vmcnt(12)
	v_pk_fma_f32 v[70:71], v[78:79], v[128:129], v[70:71]
	s_waitcnt vmcnt(9)
	v_pk_fma_f32 v[72:73], v[80:81], v[130:131], v[72:73]
	s_waitcnt vmcnt(8)
	v_pk_fma_f32 v[70:71], v[82:83], v[132:133], v[70:71]
	s_waitcnt vmcnt(5)
	v_pk_fma_f32 v[72:73], v[84:85], v[134:135], v[72:73]
	s_waitcnt vmcnt(4)
	v_pk_fma_f32 v[70:71], v[86:87], v[136:137], v[70:71]
	s_waitcnt vmcnt(1)
	v_pk_fma_f32 v[72:73], v[88:89], v[138:139], v[72:73]
	s_waitcnt vmcnt(0)
	v_pk_fma_f32 v[70:71], v[90:91], v[140:141], v[70:71]
	v_pk_add_f32 v[38:39], v[70:71], v[72:73]
	s_nop 0
	v_add_f32_e32 v38, v38, v39
	ds_write_b32 v3, v38 offset:8192
	s_waitcnt lgkmcnt(0)
	s_barrier
	s_and_saveexec_b64 s[20:21], vcc
	s_cbranch_execz .LBB0_18
	s_mulk_i32 s2, 0x1800
	s_add_i32 s2, s2, s18
	v_add_u32_e32 v38, s2, v2
	v_ashrrev_i32_e32 v39, 31, v38
	v_lshlrev_b64 v[38:39], 2, v[38:39]
	v_lshl_add_u64 v[40:41], s[8:9], 0, v[38:39]
	global_load_dword v56, v[40:41], off
	v_add_u32_e32 v46, 0x2000, v75
	v_add_u32_e32 v54, 0x2400, v75
	ds_read2_b32 v[40:41], v46 offset1:32
	ds_read2_b32 v[42:43], v46 offset0:64 offset1:96
	ds_read2_b32 v[44:45], v46 offset0:128 offset1:160
	ds_read2_b32 v[46:47], v46 offset0:192 offset1:224
	ds_read2_b32 v[48:49], v54 offset1:32
	ds_read2_b32 v[50:51], v54 offset0:64 offset1:96
	ds_read2_b32 v[52:53], v54 offset0:128 offset1:160
	ds_read2_b32 v[54:55], v54 offset0:192 offset1:224
	v_lshl_add_u64 v[38:39], s[4:5], 0, v[38:39]
	s_waitcnt vmcnt(0) lgkmcnt(7)
	v_add_f32_e32 v40, v56, v40
	v_add_f32_e32 v40, v40, v41
	s_waitcnt lgkmcnt(6)
	v_add_f32_e32 v40, v40, v42
	v_add_f32_e32 v40, v40, v43
	s_waitcnt lgkmcnt(5)
	v_add_f32_e32 v40, v40, v44
	v_add_f32_e32 v40, v40, v45
	s_waitcnt lgkmcnt(4)
	v_add_f32_e32 v40, v40, v46
	v_add_f32_e32 v40, v40, v47
	s_waitcnt lgkmcnt(3)
	v_add_f32_e32 v40, v40, v48
	v_add_f32_e32 v40, v40, v49
	s_waitcnt lgkmcnt(2)
	v_add_f32_e32 v40, v40, v50
	v_add_f32_e32 v40, v40, v51
	s_waitcnt lgkmcnt(1)
	v_add_f32_e32 v40, v40, v52
	v_add_f32_e32 v40, v40, v53
	s_waitcnt lgkmcnt(0)
	v_add_f32_e32 v40, v40, v54
	v_add_f32_e32 v40, v40, v55
	global_store_dword v[38:39], v40, off
	s_branch .LBB0_18
